# attention: reference max folded into the QK accumulator init (S-m computed by the MFMA), common softmax path has no subtracts / alpha
# speedup vs baseline: 1.0005x; 1.0005x over previous
; #define GAS __attribute__((address_space(1)))
; #define LAS __attribute__((address_space(3)))
; #define DUP(k, stmt) do { stmt; if (((MK_DUP) >> (k)) & 1u) { stmt; } } while (0)
; DI void u_attn2(Frame& F, int h, int qb, int sp, int ntile) {
;     int tid_ = F.tid; asm volatile("" : "+v"(tid_));
;     unsigned char* ws = F.ws; const int tid = tid_, lane = tid & 63, w = F.wave, g4 = lane >> 4, lc = lane & 15;
;     LAS bf16* Ks = (LAS bf16*)F.lds; LAS bf16* Vs = Ks + 64 * 200;
;     const bf16* QM = (const bf16*)(ws + WS_QM); const bf16* KM = (const bf16*)(ws + WS_KM) + h * 192; const bf16* VT = (const bf16*)(ws + WS_VT) + (size_t)(h * 128) * S;
;     const int q0 = qb * 256 + w * 32, cw = 4 * qb + (w >> 1);
;     bf16x8 qf[2][6];
; #pragma unroll
;     for (int qq = 0; qq < 2; ++qq)
; #pragma unroll
;         for (int ks = 0; ks < 6; ++ks) qf[qq][ks] = *(const GAS bf16x8*)(QM + (size_t)(q0 + qq * 16 + lc) * 768 + h * 192 + ks * 32 + g4 * 8);
;     f32x4 o[8][2]; float mrun[2], lrun[2];
; #pragma unroll
;     for (int db = 0; db < 8; ++db)
; #pragma unroll
;         for (int qq = 0; qq < 2; ++qq) o[db][qq] = (f32x4){0.f, 0.f, 0.f, 0.f};
;     mrun[0] = mrun[1] = -1e30f; lrun[0] = lrun[1] = 0.f;
;     u32x4 kreg[3], vreg[2];
;     const int kt0 = 16 * sp;
; __global__ void __launch_bounds__(NTHR, 2) mk_fwd(Args args) {
;     ...
;                 { const int* tab = (const int*)(ws + WS_ATAB);
;                   for (int r = 0; r * NB < ATT_NSUB; ++r) { const int pos = (r & 1) ? NB - 1 - b : b; const int i = r * NB + pos;
;                       if (i < ATT_NSUB) { const int e = tab[i]; DUP(0, u_attn2(F, e & 3, (e >> 2) & 31, (e >> 7) & 31, e >> 12)); } } }
.LBB0_2232:
	s_bitcmp0_b32 s44, 0
	s_cselect_b32 s31, s9, s41
	s_add_i32 s30, s31, s30
	s_cmpk_gt_i32 s30, 0x23f
	s_cbranch_scc1 .LBB0_2231
	s_ashr_i32 s31, s30, 31
	s_lshl_b64 s[30:31], s[30:31], 2
	s_add_u32 s30, s25, s30
	s_addc_u32 s31, s40, s31
	v_mov_b64_e32 v[2:3], s[30:31]
	flat_load_dword v138, v[2:3]
	v_mov_b32_e32 v158, v159
	v_mov_b32_e32 v20, v19
	v_mov_b32_e32 v21, v19
	v_mov_b32_e32 v18, v19
	v_mov_b64_e32 v[64:65], v[20:21]
	v_mov_b64_e32 v[56:57], v[20:21]
	v_mov_b64_e32 v[60:61], v[20:21]
	v_mov_b64_e32 v[68:69], v[20:21]
	v_mov_b64_e32 v[136:137], v[20:21]
	v_mov_b64_e32 v[120:121], v[20:21]
	v_mov_b64_e32 v[108:109], v[20:21]
	v_mov_b64_e32 v[104:105], v[20:21]
	v_mov_b64_e32 v[100:101], v[20:21]
	v_mov_b64_e32 v[96:97], v[20:21]
	v_mov_b64_e32 v[92:93], v[20:21]
	v_mov_b64_e32 v[88:89], v[20:21]
	v_mov_b64_e32 v[84:85], v[20:21]
	v_mov_b64_e32 v[80:81], v[20:21]
	v_mov_b64_e32 v[72:73], v[20:21]
	v_mov_b64_e32 v[76:77], v[20:21]
	v_bfe_u32 v2, v158, 4, 2
	s_mov_b32 s46, 0
	v_mov_b32_e32 v164, 0xf149f2ca
	v_mov_b32_e32 v165, 0
	v_mov_b32_e32 v163, 0
	v_mov_b32_e32 v162, 0xf149f2ca
	v_mov_b64_e32 v[62:63], v[18:19]
	v_mov_b64_e32 v[54:55], v[18:19]
	v_mov_b64_e32 v[58:59], v[18:19]
	v_mov_b64_e32 v[66:67], v[18:19]
	v_mov_b64_e32 v[134:135], v[18:19]
	v_mov_b64_e32 v[118:119], v[18:19]
	v_mov_b64_e32 v[106:107], v[18:19]
	v_mov_b64_e32 v[102:103], v[18:19]
	v_mov_b64_e32 v[98:99], v[18:19]
	v_mov_b64_e32 v[94:95], v[18:19]
	v_mov_b64_e32 v[90:91], v[18:19]
	v_mov_b64_e32 v[86:87], v[18:19]
	v_mov_b64_e32 v[82:83], v[18:19]
	v_mov_b64_e32 v[78:79], v[18:19]
	v_mov_b64_e32 v[70:71], v[18:19]
	v_and_b32_e32 v161, 15, v158
	v_lshlrev_b32_e32 v160, 3, v2
	v_mov_b64_e32 v[74:75], v[18:19]
	s_waitcnt vmcnt(0) lgkmcnt(0)
	v_ashrrev_i32_e32 v179, 12, v138
	v_and_b32_e32 v178, 3, v138
	v_bfe_u32 v177, v138, 2, 5
	v_bfe_u32 v176, v138, 7, 5
	v_cmp_lt_i32_e32 vcc, 0, v179
	s_and_saveexec_b64 s[30:31], vcc
	s_cbranch_execz .LBB0_2245
	v_mul_u32_u24_e32 v3, 0xc0, v178
	v_lshl_add_u32 v4, v177, 8, s42
	v_lshlrev_b32_e32 v18, 1, v3
	v_or_b32_e32 v30, v4, v161
	v_lshl_add_u64 v[4:5], s[12:13], 0, v[18:19]
	v_lshlrev_b32_e32 v2, 4, v2
	v_mov_b32_e32 v3, v19
	v_lshl_add_u64 v[20:21], v[4:5], 0, v[2:3]
	s_movk_i32 s38, 0x600
	v_mad_i64_i32 v[26:27], s[36:37], v30, s38, v[20:21]
	v_or_b32_e32 v30, 16, v30
	v_mad_i64_i32 v[20:21], s[36:37], v30, s38, v[20:21]
	s_mov_b32 s36, 0x2aaaaaab
	global_load_dwordx4 v[2:5], v[26:27], off
	global_load_dwordx4 v[6:9], v[26:27], off offset:64
	global_load_dwordx4 v[10:13], v[26:27], off offset:128
	global_load_dwordx4 v[14:17], v[26:27], off offset:192
	global_load_dwordx4 v[22:25], v[26:27], off offset:256
	s_nop 0
	global_load_dwordx4 v[26:29], v[26:27], off offset:320
	s_nop 0
	global_load_dwordx4 v[30:33], v[20:21], off
	global_load_dwordx4 v[34:37], v[20:21], off offset:64
	global_load_dwordx4 v[38:41], v[20:21], off offset:128
	global_load_dwordx4 v[42:45], v[20:21], off offset:192
	global_load_dwordx4 v[46:49], v[20:21], off offset:256
	global_load_dwordx4 v[50:53], v[20:21], off offset:320
	v_mul_hi_i32 v20, v158, s36
	v_lshrrev_b32_e32 v21, 31, v20
	v_ashrrev_i32_e32 v20, 2, v20
	v_add_u32_e32 v80, v20, v21
	v_add_u32_e32 v20, 0x200, v158
	v_mul_hi_i32 v21, v20, s36
	v_lshrrev_b32_e32 v54, 31, v21
	v_ashrrev_i32_e32 v21, 2, v21
	v_add_u32_e32 v81, v21, v54
	v_add_u32_e32 v54, 0x400, v158
	v_mul_hi_i32 v21, v54, s36
	v_lshrrev_b32_e32 v55, 31, v21
	v_ashrrev_i32_e32 v21, 2, v21
	v_add_u32_e32 v82, v21, v55
	s_movk_i32 s39, 0xffe8
	v_mad_u64_u32 v[54:55], s[36:37], v82, s39, v[54:55]
	v_lshlrev_b32_e32 v74, 21, v178
	v_mov_b32_e32 v75, v19
	v_ashrrev_i32_e32 v56, 3, v158
	v_ashrrev_i32_e32 v60, 3, v20
	v_lshl_add_u64 v[74:75], s[18:19], 0, v[74:75]
	v_lshlrev_b32_e32 v76, 11, v176
	v_mov_b32_e32 v77, v19
	v_lshlrev_b32_e32 v55, 4, v158
	v_ashrrev_i32_e32 v57, 31, v56
	v_ashrrev_i32_e32 v61, 31, v60
	v_mad_u64_u32 v[20:21], s[36:37], v81, s39, v[20:21]
	v_lshl_add_u64 v[74:75], v[74:75], 0, v[76:77]
	v_and_b32_e32 v76, 0x70, v55
	v_lshlrev_b64 v[58:59], 14, v[56:57]
	v_lshlrev_b64 v[62:63], 14, v[60:61]
	v_lshlrev_b32_e32 v64, 3, v54
	v_lshlrev_b32_e32 v21, 10, v176
	v_lshl_add_u64 v[74:75], v[74:75], 0, v[76:77]
	v_ashrrev_i32_e32 v65, 31, v64
	v_lshlrev_b32_e32 v66, 3, v20
	v_mad_u64_u32 v[68:69], s[36:37], v80, s39, v[158:159]
	v_lshl_add_u64 v[72:73], s[16:17], 0, v[18:19]
	v_lshl_add_u64 v[78:79], v[74:75], 0, v[62:63]
	v_lshl_add_u64 v[74:75], v[74:75], 0, v[58:59]
	v_add_u32_e32 v61, v82, v21
	v_ashrrev_i32_e32 v67, 31, v66
	v_mad_i64_i32 v[74:75], s[36:37], v61, s38, v[72:73]
	v_lshlrev_b64 v[64:65], 1, v[64:65]
	v_add_u32_e32 v69, v81, v21
	v_lshlrev_b32_e32 v70, 3, v68
	v_lshl_add_u64 v[74:75], v[74:75], 0, v[64:65]
	v_mad_i64_i32 v[78:79], s[36:37], v69, s38, v[72:73]
	v_lshlrev_b64 v[66:67], 1, v[66:67]
	v_ashrrev_i32_e32 v71, 31, v70
	v_lshl_add_u64 v[78:79], v[78:79], 0, v[66:67]
	v_add_u32_e32 v74, v21, v80
	v_mad_i64_i32 v[72:73], s[36:37], v74, s38, v[72:73]
	v_lshlrev_b64 v[70:71], 1, v[70:71]
	v_lshl_add_u64 v[72:73], v[72:73], 0, v[70:71]
	v_and_b32_e32 v21, 48, v158
	v_add_u32_e32 v73, s11, v21
	v_mov_b32_e32 v21, s11
	s_movk_i32 s36, 0x190
	v_mad_u32_u24 v77, v161, s90, v21
	v_mul_lo_u32 v21, v80, s36
	v_add_u32_e32 v79, s11, v21
	v_mul_lo_u32 v21, v81, s36
	v_lshlrev_b32_e32 v81, 4, v20
	v_mul_lo_u32 v20, v82, s36
	v_add_u32_e32 v82, s11, v20
	v_or_b32_e32 v20, 16, v161
	v_mul_u32_u24_e32 v86, 0x90, v20
	v_mov_b32_e32 v20, 0x3d000000
	v_add_u32_e32 v80, s11, v21
	v_mul_lo_u32 v84, v56, s90
	v_lshl_or_b32 v20, v178, 21, v20
	v_mov_b32_e32 v21, v19
	v_lshlrev_b32_e32 v56, 4, v138
; #define GAS __attribute__((address_space(1)))
; #define LAS __attribute__((address_space(3)))
; DI void u_attn2(Frame& F, int h, int qb, int sp, int ntile) {
;     ...
;     unsigned char* ws = F.ws; const int tid = tid_, lane = tid & 63, w = F.wave, g4 = lane >> 4, lc = lane & 15;
;     LAS bf16* Ks = (LAS bf16*)F.lds; LAS bf16* Vs = Ks + 64 * 200;
;     const bf16* QM = (const bf16*)(ws + WS_QM); const bf16* KM = (const bf16*)(ws + WS_KM) + h * 192; const bf16* VT = (const bf16*)(ws + WS_VT) + (size_t)(h * 128) * S;
;     const int q0 = qb * 256 + w * 32, cw = 4 * qb + (w >> 1);
;     bf16x8 qf[2][6];
; #pragma unroll
;     for (int qq = 0; qq < 2; ++qq)
; #pragma unroll
;         for (int ks = 0; ks < 6; ++ks) qf[qq][ks] = *(const GAS bf16x8*)(QM + (size_t)(q0 + qq * 16 + lc) * 768 + h * 192 + ks * 32 + g4 * 8);
;     f32x4 o[8][2]; float mrun[2], lrun[2];
; #pragma unroll
;     for (int db = 0; db < 8; ++db)
; #pragma unroll
;         for (int qq = 0; qq < 2; ++qq) o[db][qq] = (f32x4){0.f, 0.f, 0.f, 0.f};
;     mrun[0] = mrun[1] = -1e30f; lrun[0] = lrun[1] = 0.f;
;     u32x4 kreg[3], vreg[2];
;     const int kt0 = 16 * sp;
;     ...
;     AT_LOAD(kt0)
	v_lshlrev_b32_e32 v83, 4, v54
	v_lshl_add_u64 v[54:55], v[20:21], 0, v[62:63]
	v_and_b32_e32 v56, 0xf800, v56
	v_mov_b32_e32 v57, v19
	v_lshl_add_u64 v[20:21], v[20:21], 0, v[58:59]
	v_lshl_add_u64 v[168:169], v[20:21], 0, v[56:57]
	v_mad_i64_i32 v[20:21], s[36:37], v61, s38, v[64:65]
	v_lshl_add_u64 v[20:21], v[20:21], 0, v[18:19]
	s_mov_b64 s[48:49], 0x3c418000
	v_lshl_add_u64 v[170:171], v[20:21], 0, s[48:49]
	v_mad_i64_i32 v[20:21], s[36:37], v69, s38, v[66:67]
	v_lshl_add_u64 v[20:21], v[20:21], 0, v[18:19]
	v_lshl_add_u64 v[172:173], v[20:21], 0, s[48:49]
	v_mad_i64_i32 v[20:21], s[36:37], v74, s38, v[70:71]
	v_lshl_add_u64 v[20:21], v[20:21], 0, v[18:19]
	v_add_u32_e32 v72, s11, v76
	v_mul_u32_u24_e32 v75, 0x90, v161
	v_add_u32_e32 v78, s11, v160
	v_lshlrev_b32_e32 v68, 4, v68
	v_mul_lo_u32 v60, v60, s90
	v_mul_u32_u24_e32 v85, 0x1a0, v161
	v_lshl_add_u64 v[166:167], v[54:55], 0, v[56:57]
	v_lshl_add_u64 v[174:175], v[20:21], 0, s[48:49]
	v_mov_b32_e32 v20, v19
	v_mov_b32_e32 v21, v19
	v_or_b32_e32 v166, v166, v76
	v_or_b32_e32 v168, v168, v76
	v_mov_b32_e32 v18, v19
	v_add_u32_e32 v182, v79, v68
	v_add_u32_e32 v183, v80, v81
	v_add_u32_e32 v184, v82, v83
	v_add_u32_e32 v185, v72, v84
	v_add_u32_e32 v186, v72, v60
	v_add_u32_e32 v187, v73, v85
	v_add_u32_e32 v188, v77, v160
	v_add_u32_e32 v189, v78, v86
	v_add_u32_e32 v190, v78, v75
	v_mov_b64_e32 v[76:77], v[20:21]
	v_mov_b64_e32 v[72:73], v[20:21]
	v_mov_b64_e32 v[80:81], v[20:21]
	v_mov_b64_e32 v[84:85], v[20:21]
	v_mov_b64_e32 v[88:89], v[20:21]
	v_mov_b64_e32 v[92:93], v[20:21]
	v_mov_b64_e32 v[96:97], v[20:21]
	v_mov_b64_e32 v[100:101], v[20:21]
	v_mov_b64_e32 v[104:105], v[20:21]
	v_mov_b64_e32 v[108:109], v[20:21]
	v_mov_b64_e32 v[120:121], v[20:21]
	v_mov_b64_e32 v[136:137], v[20:21]
	v_mov_b64_e32 v[68:69], v[20:21]
	v_mov_b64_e32 v[60:61], v[20:21]
	v_mov_b64_e32 v[56:57], v[20:21]
	v_mov_b64_e32 v[64:65], v[20:21]
	v_lshl_add_u32 v180, v177, 2, s43
	v_lshlrev_b32_e32 v181, 4, v176
	v_mov_b32_e32 v163, 0
	v_mov_b32_e32 v162, 0
	s_mov_b64 s[36:37], 0
	v_mov_b64_e32 v[74:75], v[18:19]
	v_mov_b64_e32 v[70:71], v[18:19]
	v_mov_b64_e32 v[78:79], v[18:19]
	v_mov_b64_e32 v[82:83], v[18:19]
	v_mov_b64_e32 v[86:87], v[18:19]
	v_mov_b64_e32 v[90:91], v[18:19]
	v_mov_b64_e32 v[94:95], v[18:19]
	v_mov_b64_e32 v[98:99], v[18:19]
	v_mov_b64_e32 v[102:103], v[18:19]
	v_mov_b64_e32 v[106:107], v[18:19]
	v_mov_b64_e32 v[118:119], v[18:19]
	v_mov_b64_e32 v[134:135], v[18:19]
	v_mov_b32_e32 v164, 0
	v_mov_b32_e32 v165, 0
	v_mov_b64_e32 v[66:67], v[18:19]
	v_mov_b64_e32 v[58:59], v[18:19]
	v_mov_b64_e32 v[54:55], v[18:19]
	v_mov_b64_e32 v[62:63], v[18:19]
	v_readfirstlane_b32 s38, v178
	v_readfirstlane_b32 s39, v176
	v_readfirstlane_b32 s45, v179
	s_mul_i32 s47, s38, 0x180
	s_mul_i32 s37, s39, 0x180000
	s_add_i32 s47, s47, s37
	s_add_u32 s48, s16, s47
	s_addc_u32 s49, s17, 0
	s_lshl_b32 s38, s38, 21
	s_lshl_b32 s39, s39, 11
	s_add_i32 s38, s38, s39
	s_add_u32 s36, s18, s38
	s_addc_u32 s37, s19, 0
	v_and_b32_e32 v114, 63, v158
	v_mul_u32_u24_e32 v111, 0xa0, v161
	v_lshl_add_u32 v111, v160, 1, v111
	v_add_u32_e32 v111, s11, v111
	s_lshl_b32 s47, s24, 6
	v_add_u32_e32 v115, s47, v114
	v_mul_u32_u24_e32 v128, 0x4ed, v115
	v_lshrrev_b32_e32 v128, 15, v128
	v_mul_u32_u24_e32 v129, 26, v128
	v_sub_u32_e32 v129, v115, v129
	v_min_u32_e32 v129, 23, v129
	v_and_b32_e32 v117, 35, v128
	v_and_b32_e32 v130, 12, v128
	v_lshl_or_b32 v117, v130, 1, v117
	v_and_b32_e32 v130, 16, v128
	v_lshrrev_b32_e32 v130, 2, v130
	v_or_b32_e32 v117, v117, v130
	v_mul_u32_u24_e32 v117, 0x600, v117
	v_lshl_add_u32 v122, v129, 4, v117
	v_add_u32_e32 v115, 0x200, v115
	v_mul_u32_u24_e32 v128, 0x4ed, v115
	v_lshrrev_b32_e32 v128, 15, v128
	v_mul_u32_u24_e32 v129, 26, v128
	v_sub_u32_e32 v129, v115, v129
	v_min_u32_e32 v129, 23, v129
	v_and_b32_e32 v117, 35, v128
	v_and_b32_e32 v130, 12, v128
	v_lshl_or_b32 v117, v130, 1, v117
	v_and_b32_e32 v130, 16, v128
	v_lshrrev_b32_e32 v130, 2, v130
	v_or_b32_e32 v117, v117, v130
	v_mul_u32_u24_e32 v117, 0x600, v117
	v_lshl_add_u32 v123, v129, 4, v117
	v_add_u32_e32 v115, 0x200, v115
	v_mul_u32_u24_e32 v128, 0x4ed, v115
	v_lshrrev_b32_e32 v128, 15, v128
	v_mul_u32_u24_e32 v129, 26, v128
	v_sub_u32_e32 v129, v115, v129
	v_min_u32_e32 v129, 23, v129
	v_and_b32_e32 v117, 35, v128
	v_and_b32_e32 v130, 12, v128
	v_lshl_or_b32 v117, v130, 1, v117
	v_and_b32_e32 v130, 16, v128
	v_lshrrev_b32_e32 v130, 2, v130
	v_or_b32_e32 v117, v117, v130
	v_mul_u32_u24_e32 v117, 0x600, v117
	v_lshl_add_u32 v124, v129, 4, v117
	v_add_u32_e32 v115, s47, v114
	v_mul_u32_u24_e32 v128, 0x667, v115
	v_lshrrev_b32_e32 v128, 14, v128
	v_mul_u32_u24_e32 v129, 10, v128
	v_sub_u32_e32 v129, v115, v129
	v_min_u32_e32 v129, 7, v129
	v_lshlrev_b32_e32 v128, 14, v128
	v_lshl_add_u32 v125, v129, 4, v128
	v_add_u32_e32 v115, 0x200, v115
	v_mul_u32_u24_e32 v128, 0x667, v115
	v_lshrrev_b32_e32 v128, 14, v128
	v_mul_u32_u24_e32 v129, 10, v128
	v_sub_u32_e32 v129, v115, v129
	v_min_u32_e32 v129, 7, v129
	v_lshlrev_b32_e32 v128, 14, v128
	v_lshl_add_u32 v126, v129, 4, v128
	s_cmp_lt_u32 s24, 2
	s_cbranch_scc0 .Latt_xv
	s_addk_i32 s47, 0x600
	v_add_u32_e32 v115, s47, v114
	v_mul_u32_u24_e32 v128, 0x4ed, v115
	v_lshrrev_b32_e32 v128, 15, v128
	v_mul_u32_u24_e32 v129, 26, v128
	v_sub_u32_e32 v129, v115, v129
	v_min_u32_e32 v129, 23, v129
	v_and_b32_e32 v117, 35, v128
	v_and_b32_e32 v130, 12, v128
	v_lshl_or_b32 v117, v130, 1, v117
	v_and_b32_e32 v130, 16, v128
	v_lshrrev_b32_e32 v130, 2, v130
	v_or_b32_e32 v117, v117, v130
	v_mul_u32_u24_e32 v117, 0x600, v117
	v_lshl_add_u32 v127, v129, 4, v117
	s_branch .Latt_xdone

; DI void u_attn2(Frame& F, int h, int qb, int sp, int ntile) {
;     ...
;     mrun[0] = mrun[1] = -1e30f; lrun[0] = lrun[1] = 0.f;
;     u32x4 kreg[3], vreg[2];
;     const int kt0 = 16 * sp;
;     ...
;     AT_LOAD(kt0)
.Latt_xdone:
	v_mov_b32_e32 v114, 0
	v_mov_b32_e32 v115, 0
	v_mov_b32_e32 v116, 0
	v_mov_b32_e32 v117, 0
	v_mov_b32_e32 v128, 0
	v_mov_b32_e32 v129, 0
	v_mov_b32_e32 v130, 0
	v_mov_b32_e32 v131, 0
	s_lshl_b32 vcc_lo, s24, 10
	s_add_i32 vcc_lo, vcc_lo, s11
	s_mov_b32 m0, vcc_lo
	s_nop 0
	global_load_lds_dwordx4 v122, s[48:49]
	s_add_i32 m0, m0, 0x2000
	s_nop 0
	global_load_lds_dwordx4 v123, s[48:49]
	s_add_i32 m0, m0, 0x2000
	s_nop 0
	global_load_lds_dwordx4 v124, s[48:49]
	s_cmp_lt_u32 s24, 2
	s_cbranch_scc0 .Latt_p1
	s_add_i32 m0, vcc_lo, 0x6000
	s_nop 0
	global_load_lds_dwordx4 v127, s[48:49]

; #define LAS __attribute__((address_space(3)))
; DI void u_attn2(Frame& F, int h, int qb, int sp, int ntile) {
;     ...
;     for (int t = 0; t < ntile; ++t) {
;         const int kt = kt0 + t;
;         __syncthreads();
; #pragma unroll
;         for (int i = 0; i < 3; ++i) { const int p = tid + 512 * i, r = p / 24, cc = p - r * 24; *(LAS u32x4*)(Ks + r * 200 + cc * 8) = kreg[i]; }
; #pragma unroll
;         for (int i = 0; i < 2; ++i) { const int p = tid + 512 * i, r = p >> 3, cc = p & 7; *(LAS u32x4*)(Vs + r * 72 + cc * 8) = vreg[i]; }
;         __syncthreads();
;         if (t + 1 < ntile) AT_LOAD(kt + 1)
.LBB0_2237:
	s_barrier
	s_add_i32 s39, s47, 0xb800
	s_cmp_eq_u32 s39, 0x22800
	s_cselect_b32 s39, 0, s39
	s_add_i32 s38, s39, 0xb800
	s_cmp_eq_u32 s38, 0x22800
	s_cselect_b32 s38, 0, s38
	v_add_u32_e32 v112, s47, v187
	v_add_u32_e32 v110, s38, v111
	v_mov_b32_e32 v234, 0x42800000
	s_cmp_lt_i32 s24, 4
	s_cbranch_scc0 .Latt_gB
	s_lshl_b32 vcc_lo, s24, 10
	s_add_i32 vcc_lo, vcc_lo, s11
	s_add_i32 vcc_hi, s46, 2
	s_cmp_lt_i32 vcc_hi, s45
	s_cbranch_scc0 .Latt_vonly_A
	s_add_i32 m0, s38, vcc_lo
	s_nop 0
	global_load_lds_dwordx4 v122, s[48:49]
	s_add_i32 m0, m0, 0x2000
	s_nop 0
	global_load_lds_dwordx4 v123, s[48:49]
	s_add_i32 m0, m0, 0x2000
	s_nop 0
	global_load_lds_dwordx4 v124, s[48:49]
	s_branch .Latt_vjobs_A

; DI float xr16_max(float x) { float a = x, b = x; XR_SWAP("v_permlane16_swap_b32", a, b); return fmaxf(a, b); }
; DI float xr32_max(float x) { float a = x, b = x; XR_SWAP("v_permlane32_swap_b32", a, b); return fmaxf(a, b); }
; #define MFMA16(a, b, c) __builtin_amdgcn_mfma_f32_16x16x32_bf16((a), (b), (c), 0, 0, 0)
; DI void u_attn2(Frame& F, int h, int qb, int sp, int ntile) {
;     ...
;         if (kt <= cw) {
;             f32x4 s[4][2];
; #pragma unroll
;             for (int kb = 0; kb < 4; ++kb)
; #pragma unroll
;                 for (int qq = 0; qq < 2; ++qq) s[kb][qq] = (f32x4){0.f, 0.f, 0.f, 0.f};
;             {
;                 bf16x8 kfr[2][4];
; #pragma unroll
;                 for (int kb = 0; kb < 4; ++kb) kfr[0][kb] = ldfrag(Ks, 200, kb * 16, 0, lane);
; #pragma unroll
;                 for (int ks = 0; ks < 6; ++ks) {
;                     if (ks < 5) {
; #pragma unroll
;                         for (int kb = 0; kb < 4; ++kb) kfr[(ks + 1) & 1][kb] = ldfrag(Ks, 200, kb * 16, (ks + 1) * 32, lane); }
; #pragma unroll
;                     for (int kb = 0; kb < 4; ++kb)
; #pragma unroll
;                         for (int qq = 0; qq < 2; ++qq) s[kb][qq] = MFMA16(kfr[ks & 1][kb], qf[qq][ks], s[kb][qq]);
;                 }
;             }
;             bf16x8 pf[2][2];
; #pragma unroll
;             for (int qq = 0; qq < 2; ++qq) {
;                 float mx = -1e30f;
; #pragma unroll
;                 for (int kb = 0; kb < 4; ++kb) mx = fmaxf(mx, fmaxf(fmaxf(s[kb][qq][0], s[kb][qq][1]), fmaxf(s[kb][qq][2], s[kb][qq][3])));
;                 mx = xr32_max(xr16_max(mx));
;                 const float mn = fmaxf(mrun[qq], mx), alpha = __builtin_amdgcn_exp2f(mrun[qq] - mn); mrun[qq] = mn;
.Latt_A_qk:
	v_cmp_lt_i32_e32 vcc, s46, v179
	s_cbranch_vccz .LBB0_2236
	v_add_u32_e32 v18, s46, v181
	v_cmp_le_i32_e32 vcc, v18, v180
	s_cbranch_vccz .LBB0_2236
	ds_read_b128 v[138:141], v112
	ds_read_b128 v[142:145], v112 offset:6656
	ds_read_b128 v[146:149], v112 offset:13312
	ds_read_b128 v[150:153], v112 offset:19968
	ds_read_b128 v[154:157], v112 offset:64
	ds_read_b128 v[192:195], v112 offset:6720
	ds_read_b128 v[210:213], v112 offset:13376
	ds_read_b128 v[214:217], v112 offset:20032
	s_waitcnt lgkmcnt(7)
	v_mfma_f32_16x16x32_bf16 v[218:221], v[138:141], v[2:5], v[114:117]
	ds_read_b128 v[244:247], v112 offset:128
	ds_read_b128 v[248:251], v112 offset:6784
	ds_read_b128 v[198:201], v112 offset:13440
	ds_read_b128 v[230:233], v112 offset:20096
	v_mov_b32_e32 v234, 0x42800000
	v_mfma_f32_16x16x32_bf16 v[138:141], v[138:141], v[30:33], v[128:131]
	s_waitcnt lgkmcnt(10)
	v_mfma_f32_16x16x32_bf16 v[222:225], v[142:145], v[2:5], v[114:117]
	v_mfma_f32_16x16x32_bf16 v[142:145], v[142:145], v[30:33], v[128:131]
	s_waitcnt lgkmcnt(9)
	v_mfma_f32_16x16x32_bf16 v[226:229], v[146:149], v[2:5], v[114:117]
	s_waitcnt lgkmcnt(7)
	v_mfma_f32_16x16x32_bf16 v[218:221], v[154:157], v[6:9], v[218:221]
	v_mfma_f32_16x16x32_bf16 v[146:149], v[146:149], v[30:33], v[128:131]
	v_mfma_f32_16x16x32_bf16 v[240:243], v[150:153], v[2:5], v[114:117]
	v_mfma_f32_16x16x32_bf16 v[150:153], v[150:153], v[30:33], v[128:131]
	v_mfma_f32_16x16x32_bf16 v[138:141], v[154:157], v[34:37], v[138:141]
	s_waitcnt lgkmcnt(6)
	v_mfma_f32_16x16x32_bf16 v[154:157], v[192:195], v[6:9], v[222:225]
	v_mfma_f32_16x16x32_bf16 v[142:145], v[192:195], v[34:37], v[142:145]
	s_waitcnt lgkmcnt(5)
	v_mfma_f32_16x16x32_bf16 v[192:195], v[210:213], v[6:9], v[226:229]
	s_waitcnt lgkmcnt(3)
	v_mfma_f32_16x16x32_bf16 v[218:221], v[244:247], v[10:13], v[218:221]
	v_mfma_f32_16x16x32_bf16 v[146:149], v[210:213], v[34:37], v[146:149]
	v_mfma_f32_16x16x32_bf16 v[210:213], v[214:217], v[6:9], v[240:243]
	v_mfma_f32_16x16x32_bf16 v[150:153], v[214:217], v[34:37], v[150:153]
	ds_read_b128 v[214:217], v112 offset:192
	ds_read_b128 v[222:225], v112 offset:6848
	ds_read_b128 v[226:229], v112 offset:13504
	ds_read_b128 v[240:243], v112 offset:20160
	v_mfma_f32_16x16x32_bf16 v[138:141], v[244:247], v[38:41], v[138:141]
	s_waitcnt lgkmcnt(6)
	v_mfma_f32_16x16x32_bf16 v[154:157], v[248:251], v[10:13], v[154:157]
	v_mfma_f32_16x16x32_bf16 v[142:145], v[248:251], v[38:41], v[142:145]
	s_waitcnt lgkmcnt(5)
	v_mfma_f32_16x16x32_bf16 v[192:195], v[198:201], v[10:13], v[192:195]
	s_waitcnt lgkmcnt(3)
	v_mfma_f32_16x16x32_bf16 v[218:221], v[214:217], v[14:17], v[218:221]
	v_mfma_f32_16x16x32_bf16 v[146:149], v[198:201], v[38:41], v[146:149]
	v_mfma_f32_16x16x32_bf16 v[198:201], v[230:233], v[10:13], v[210:213]
	v_mfma_f32_16x16x32_bf16 v[150:153], v[230:233], v[38:41], v[150:153]
	s_nop 1
	ds_read_b128 v[210:213], v112 offset:256
	ds_read_b128 v[230:233], v112 offset:6912
	ds_read_b128 v[244:247], v112 offset:13568
	ds_read_b128 v[248:251], v112 offset:20224
	v_mfma_f32_16x16x32_bf16 v[138:141], v[214:217], v[42:45], v[138:141]
	s_waitcnt lgkmcnt(6)
	v_mfma_f32_16x16x32_bf16 v[154:157], v[222:225], v[14:17], v[154:157]
	v_mfma_f32_16x16x32_bf16 v[142:145], v[222:225], v[42:45], v[142:145]
	s_waitcnt lgkmcnt(5)
	v_mfma_f32_16x16x32_bf16 v[192:195], v[226:229], v[14:17], v[192:195]
	s_waitcnt lgkmcnt(3)
	v_mfma_f32_16x16x32_bf16 v[218:221], v[210:213], v[22:25], v[218:221]
	v_mfma_f32_16x16x32_bf16 v[198:201], v[240:243], v[14:17], v[198:201]
	v_mfma_f32_16x16x32_bf16 v[150:153], v[240:243], v[42:45], v[150:153]
	v_mfma_f32_16x16x32_bf16 v[138:141], v[210:213], v[46:49], v[138:141]
	s_waitcnt lgkmcnt(2)
	v_mfma_f32_16x16x32_bf16 v[154:157], v[230:233], v[22:25], v[154:157]
	v_mfma_f32_16x16x32_bf16 v[146:149], v[226:229], v[42:45], v[146:149]
	ds_read_b128 v[214:217], v112 offset:320
	ds_read_b128 v[222:225], v112 offset:6976
	ds_read_b128 v[226:229], v112 offset:13632
	ds_read_b128 v[240:243], v112 offset:20288
	v_mfma_f32_16x16x32_bf16 v[142:145], v[230:233], v[46:49], v[142:145]
	s_waitcnt lgkmcnt(5)
	v_mfma_f32_16x16x32_bf16 v[192:195], v[244:247], v[22:25], v[192:195]
	s_waitcnt lgkmcnt(3)
	v_mfma_f32_16x16x32_bf16 v[218:221], v[214:217], v[26:29], v[218:221]
	v_mfma_f32_16x16x32_bf16 v[198:201], v[248:251], v[22:25], v[198:201]
	v_mfma_f32_16x16x32_bf16 v[230:233], v[248:251], v[46:49], v[150:153]
	v_mfma_f32_16x16x32_bf16 v[150:153], v[214:217], v[50:53], v[138:141]
	s_waitcnt lgkmcnt(2)
	v_mfma_f32_16x16x32_bf16 v[214:217], v[222:225], v[26:29], v[154:157]
	v_mfma_f32_16x16x32_bf16 v[210:213], v[244:247], v[46:49], v[146:149]
	v_mfma_f32_16x16x32_bf16 v[146:149], v[222:225], v[50:53], v[142:145]
	s_waitcnt lgkmcnt(1)
	v_mfma_f32_16x16x32_bf16 v[222:225], v[226:229], v[26:29], v[192:195]
	s_waitcnt lgkmcnt(0)
	v_mfma_f32_16x16x32_bf16 v[154:157], v[240:243], v[26:29], v[198:201]
	v_mfma_f32_16x16x32_bf16 v[138:141], v[240:243], v[50:53], v[230:233]
	s_nop 1
	v_mfma_f32_16x16x32_bf16 v[142:145], v[226:229], v[50:53], v[210:213]
	s_nop 7
	s_nop 1
	v_max3_f32 v198, v218, v219, v220
	v_max3_f32 v210, v150, v151, v152
	v_max3_f32 v199, v221, v214, v215
	v_max3_f32 v211, v153, v146, v147
	v_max3_f32 v200, v216, v217, v222
	v_max3_f32 v212, v148, v149, v142
	v_max3_f32 v201, v223, v224, v225
	v_max3_f32 v213, v143, v144, v145
	v_max3_f32 v192, v154, v155, v156
	v_max3_f32 v193, v138, v139, v140
	v_max3_f32 v198, v198, v199, v157
	v_max3_f32 v210, v210, v211, v141
	v_max3_f32 v200, v200, v201, v192
	v_max3_f32 v212, v212, v213, v193
	v_max3_f32 v18, v198, v200, s1
	v_max3_f32 v20, v210, v212, s1
	v_mov_b32_e32 v198, v18
	v_mov_b32_e32 v210, v20
	s_nop 0
	v_permlane16_swap_b32 v18, v198
	v_permlane16_swap_b32 v20, v210
	s_nop 0
	v_max_f32_e32 v18, v18, v198
	v_max_f32_e32 v20, v20, v210
	v_mov_b32_e32 v198, v18
	v_mov_b32_e32 v210, v20
	s_nop 0
	v_permlane32_swap_b32 v18, v198
	v_permlane32_swap_b32 v20, v210
	s_nop 0
	v_max_f32_e32 v18, v18, v198
	v_max_f32_e32 v20, v20, v210
	s_cmp_eq_u32 s46, 0
	v_cmp_lt_f32_e32 vcc, 0x41000000, v18
	s_cselect_b64 vcc, exec, vcc
	s_nop 0
	v_cndmask_b32_e32 v21, 0, v18, vcc
	v_cmp_lt_f32_e32 vcc, 0x41000000, v20
	s_cselect_b64 vcc, exec, vcc
	s_nop 0
	v_cndmask_b32_e32 v191, 0, v20, vcc
	v_or_b32_e32 v18, v21, v191
	v_cmp_neq_f32_e32 vcc, 0, v18
	s_cbranch_vccz .Latt_r1_A
; DI unsigned pk2(float lo, float hi) { const f32x2 v = {lo, hi}; const bf16x2_t b = __builtin_convertvector(v, bf16x2_t); return __builtin_bit_cast(unsigned, b); }
; DI float xr16_sum(float x) { float a = x, b = x; XR_SWAP("v_permlane16_swap_b32", a, b); return a + b; }
; DI float xr32_sum(float x) { float a = x, b = x; XR_SWAP("v_permlane32_swap_b32", a, b); return a + b; }
; DI void u_attn2(Frame& F, int h, int qb, int sp, int ntile) {
;     ...
;                 const float mn = fmaxf(mrun[qq], mx), alpha = __builtin_amdgcn_exp2f(mrun[qq] - mn); mrun[qq] = mn;
;                 float ps = 0.f; float p[16];
; #pragma unroll
;                 for (int kb = 0; kb < 4; ++kb)
; #pragma unroll
;                     for (int r = 0; r < 4; ++r) { p[kb * 4 + r] = __builtin_amdgcn_exp2f(s[kb][qq][r] - mn); ps += p[kb * 4 + r]; }
;                 ps = xr32_sum(xr16_sum(ps));
;                 lrun[qq] = lrun[qq] * alpha + ps;
; if (__builtin_amdgcn_ballot_w64(alpha != 1.0f) != 0ull) {
; #pragma unroll
;                     for (int db = 0; db < 8; ++db) o[db][qq] = o[db][qq] * alpha; }
; #pragma unroll
;                 for (int s2 = 0; s2 < 2; ++s2) { u32x4 pw; pw.x = pk2(p[8 * s2], p[8 * s2 + 1]); pw.y = pk2(p[8 * s2 + 2], p[8 * s2 + 3]); pw.z = pk2(p[8 * s2 + 4], p[8 * s2 + 5]); pw.w = pk2(p[8 * s2 + 6], p[8 * s2 + 7]); pf[qq][s2] = __builtin_bit_cast(bf16x8, pw); }
	v_sub_f32_e32 v218, v218, v21
	v_sub_f32_e32 v219, v219, v21
	v_sub_f32_e32 v220, v220, v21
	v_sub_f32_e32 v221, v221, v21
	v_sub_f32_e32 v214, v214, v21
	v_sub_f32_e32 v215, v215, v21
	v_sub_f32_e32 v216, v216, v21
	v_sub_f32_e32 v217, v217, v21
	v_sub_f32_e32 v222, v222, v21
	v_sub_f32_e32 v223, v223, v21
	v_sub_f32_e32 v224, v224, v21
	v_sub_f32_e32 v225, v225, v21
	v_sub_f32_e32 v154, v154, v21
	v_sub_f32_e32 v155, v155, v21
	v_sub_f32_e32 v156, v156, v21
	v_sub_f32_e32 v157, v157, v21
	v_sub_f32_e32 v150, v150, v191
	v_sub_f32_e32 v151, v151, v191
	v_sub_f32_e32 v152, v152, v191
	v_sub_f32_e32 v153, v153, v191
	v_sub_f32_e32 v146, v146, v191
	v_sub_f32_e32 v147, v147, v191
	v_sub_f32_e32 v148, v148, v191
	v_sub_f32_e32 v149, v149, v191
	v_sub_f32_e32 v142, v142, v191
	v_sub_f32_e32 v143, v143, v191
	v_sub_f32_e32 v144, v144, v191
	v_sub_f32_e32 v145, v145, v191
	v_sub_f32_e32 v138, v138, v191
	v_sub_f32_e32 v139, v139, v191
	v_sub_f32_e32 v140, v140, v191
	v_sub_f32_e32 v141, v141, v191
	v_sub_f32_e32 v18, 0, v21
	v_sub_f32_e32 v20, 0, v191
	v_min_f32_e32 v18, 0, v18
	v_min_f32_e32 v20, 0, v20
	v_exp_f32_e32 v18, v18
	v_exp_f32_e32 v20, v20
	v_add_f32_e32 v164, v164, v21
	v_add_f32_e32 v162, v162, v191
	v_sub_f32_e32 v114, v114, v21
	v_sub_f32_e32 v115, v115, v21
	v_sub_f32_e32 v116, v116, v21
	v_sub_f32_e32 v117, v117, v21
	v_sub_f32_e32 v128, v128, v191
	v_sub_f32_e32 v129, v129, v191
	v_sub_f32_e32 v130, v130, v191
	v_sub_f32_e32 v131, v131, v191
	v_pk_mul_f32 v[136:137], v[136:137], v[18:19] op_sel_hi:[1,0]
	v_pk_mul_f32 v[134:135], v[134:135], v[18:19] op_sel_hi:[1,0]
	v_pk_mul_f32 v[108:109], v[108:109], v[18:19] op_sel_hi:[1,0]
	v_pk_mul_f32 v[106:107], v[106:107], v[18:19] op_sel_hi:[1,0]
	v_pk_mul_f32 v[100:101], v[100:101], v[18:19] op_sel_hi:[1,0]
	v_pk_mul_f32 v[98:99], v[98:99], v[18:19] op_sel_hi:[1,0]
	v_pk_mul_f32 v[92:93], v[92:93], v[18:19] op_sel_hi:[1,0]
	v_pk_mul_f32 v[90:91], v[90:91], v[18:19] op_sel_hi:[1,0]
	v_pk_mul_f32 v[84:85], v[84:85], v[18:19] op_sel_hi:[1,0]
	v_pk_mul_f32 v[82:83], v[82:83], v[18:19] op_sel_hi:[1,0]
	v_pk_mul_f32 v[72:73], v[72:73], v[18:19] op_sel_hi:[1,0]
	v_pk_mul_f32 v[70:71], v[70:71], v[18:19] op_sel_hi:[1,0]
	v_pk_mul_f32 v[68:69], v[68:69], v[18:19] op_sel_hi:[1,0]
	v_pk_mul_f32 v[66:67], v[66:67], v[18:19] op_sel_hi:[1,0]
	v_pk_mul_f32 v[56:57], v[56:57], v[18:19] op_sel_hi:[1,0]
	v_pk_mul_f32 v[54:55], v[54:55], v[18:19] op_sel_hi:[1,0]
	v_pk_mul_f32 v[120:121], v[120:121], v[20:21] op_sel_hi:[1,0]
	v_pk_mul_f32 v[118:119], v[118:119], v[20:21] op_sel_hi:[1,0]
	v_pk_mul_f32 v[104:105], v[104:105], v[20:21] op_sel_hi:[1,0]
	v_pk_mul_f32 v[102:103], v[102:103], v[20:21] op_sel_hi:[1,0]
	v_pk_mul_f32 v[96:97], v[96:97], v[20:21] op_sel_hi:[1,0]
	v_pk_mul_f32 v[94:95], v[94:95], v[20:21] op_sel_hi:[1,0]
	v_pk_mul_f32 v[88:89], v[88:89], v[20:21] op_sel_hi:[1,0]
	v_pk_mul_f32 v[86:87], v[86:87], v[20:21] op_sel_hi:[1,0]
	v_pk_mul_f32 v[80:81], v[80:81], v[20:21] op_sel_hi:[1,0]
	v_pk_mul_f32 v[78:79], v[78:79], v[20:21] op_sel_hi:[1,0]
	v_pk_mul_f32 v[76:77], v[76:77], v[20:21] op_sel_hi:[1,0]
	v_pk_mul_f32 v[74:75], v[74:75], v[20:21] op_sel_hi:[1,0]
	v_pk_mul_f32 v[60:61], v[60:61], v[20:21] op_sel_hi:[1,0]
	v_pk_mul_f32 v[58:59], v[58:59], v[20:21] op_sel_hi:[1,0]
	v_pk_mul_f32 v[64:65], v[64:65], v[20:21] op_sel_hi:[1,0]
	v_pk_mul_f32 v[62:63], v[62:63], v[20:21] op_sel_hi:[1,0]
	v_mul_f32_e32 v165, v165, v18
	v_mul_f32_e32 v163, v163, v20
.Latt_r1_A:
	v_exp_f32_e32 v218, v218
	v_exp_f32_e32 v219, v219
	v_exp_f32_e32 v220, v220
	v_exp_f32_e32 v221, v221
	v_exp_f32_e32 v214, v214
	v_exp_f32_e32 v215, v215
	v_exp_f32_e32 v216, v216
	v_exp_f32_e32 v217, v217
	v_exp_f32_e32 v222, v222
	v_exp_f32_e32 v223, v223
	v_exp_f32_e32 v224, v224
	v_exp_f32_e32 v225, v225
	v_exp_f32_e32 v154, v154
	v_exp_f32_e32 v155, v155
	v_exp_f32_e32 v156, v156
	v_exp_f32_e32 v157, v157
	v_exp_f32_e32 v150, v150
	v_exp_f32_e32 v151, v151
	v_exp_f32_e32 v152, v152
	v_exp_f32_e32 v153, v153
	v_exp_f32_e32 v146, v146
	v_exp_f32_e32 v147, v147
	v_exp_f32_e32 v148, v148
	v_exp_f32_e32 v149, v149
	v_exp_f32_e32 v142, v142
	v_exp_f32_e32 v143, v143
	v_exp_f32_e32 v144, v144
	v_exp_f32_e32 v145, v145
	v_exp_f32_e32 v138, v138
	v_exp_f32_e32 v139, v139
	v_exp_f32_e32 v140, v140
	v_exp_f32_e32 v141, v141
	v_add_f32_e32 v198, v218, v219
	v_add_f32_e32 v199, v220, v221
	v_add_f32_e32 v200, v214, v215
	v_add_f32_e32 v201, v216, v217
	v_add_f32_e32 v210, v150, v151
	v_add_f32_e32 v211, v152, v153
	v_add_f32_e32 v212, v146, v147
	v_add_f32_e32 v213, v148, v149
	v_add_f32_e32 v198, v198, v222
	v_add_f32_e32 v199, v199, v223
	v_add_f32_e32 v200, v200, v224
	v_add_f32_e32 v201, v201, v225
	v_add_f32_e32 v210, v210, v142
	v_add_f32_e32 v211, v211, v143
	v_add_f32_e32 v212, v212, v144
	v_add_f32_e32 v213, v213, v145
	v_add_f32_e32 v198, v198, v154
	v_add_f32_e32 v199, v199, v155
	v_add_f32_e32 v200, v200, v156
	v_add_f32_e32 v201, v201, v157
	v_add_f32_e32 v210, v210, v138
	v_add_f32_e32 v211, v211, v139
	v_add_f32_e32 v212, v212, v140
	v_add_f32_e32 v213, v213, v141
	v_add_f32_e32 v198, v198, v199
	v_add_f32_e32 v200, v200, v201
	v_add_f32_e32 v210, v210, v211
	v_add_f32_e32 v212, v212, v213
	v_add_f32_e32 v198, v198, v200
	v_add_f32_e32 v210, v210, v212
	v_add_f32_e32 v165, v165, v198
	v_add_f32_e32 v163, v163, v210
	v_cvt_pk_bf16_f32 v198, v218, v219
	v_cvt_pk_bf16_f32 v199, v220, v221
	v_cvt_pk_bf16_f32 v200, v214, v215
	v_cvt_pk_bf16_f32 v201, v216, v217
	v_cvt_pk_bf16_f32 v192, v222, v223
	v_cvt_pk_bf16_f32 v193, v224, v225
	v_cvt_pk_bf16_f32 v194, v154, v155
	v_cvt_pk_bf16_f32 v195, v156, v157
	v_cvt_pk_bf16_f32 v210, v150, v151
	v_cvt_pk_bf16_f32 v211, v152, v153
	v_cvt_pk_bf16_f32 v212, v146, v147
	v_cvt_pk_bf16_f32 v213, v148, v149
	v_cvt_pk_bf16_f32 v142, v142, v143
	v_cvt_pk_bf16_f32 v143, v144, v145
	v_cvt_pk_bf16_f32 v144, v138, v139
	v_cvt_pk_bf16_f32 v145, v140, v141
	s_branch .LBB0_2236
; DI float xr16_max(float x) { float a = x, b = x; XR_SWAP("v_permlane16_swap_b32", a, b); return fmaxf(a, b); }
; DI float xr32_max(float x) { float a = x, b = x; XR_SWAP("v_permlane32_swap_b32", a, b); return fmaxf(a, b); }
; DI float xr16_sum(float x) { float a = x, b = x; XR_SWAP("v_permlane16_swap_b32", a, b); return a + b; }
; DI float xr32_sum(float x) { float a = x, b = x; XR_SWAP("v_permlane32_swap_b32", a, b); return a + b; }
; DI void u_attn2(Frame& F, int h, int qb, int sp, int ntile) {
;     ...
; #pragma unroll
;             for (int qq = 0; qq < 2; ++qq) {
;                 float mx = -1e30f;
; #pragma unroll
;                 for (int kb = 0; kb < 4; ++kb) mx = fmaxf(mx, fmaxf(fmaxf(s[kb][qq][0], s[kb][qq][1]), fmaxf(s[kb][qq][2], s[kb][qq][3])));
;                 mx = xr32_max(xr16_max(mx));
;                 const float mn = fmaxf(mrun[qq], mx), alpha = __builtin_amdgcn_exp2f(mrun[qq] - mn); mrun[qq] = mn;
;                 float ps = 0.f; float p[16];
; #pragma unroll
;                 for (int kb = 0; kb < 4; ++kb)
; #pragma unroll
;                     for (int r = 0; r < 4; ++r) { p[kb * 4 + r] = __builtin_amdgcn_exp2f(s[kb][qq][r] - mn); ps += p[kb * 4 + r]; }
;                 ps = xr32_sum(xr16_sum(ps));
;                 lrun[qq] = lrun[qq] * alpha + ps;
; if (__builtin_amdgcn_ballot_w64(alpha != 1.0f) != 0ull) {
; #pragma unroll
;                     for (int db = 0; db < 8; ++db) o[db][qq] = o[db][qq] * alpha; }
.Latt_gB:
	s_cmp_eq_u32 s46, 0
	s_cbranch_scc1 .Latt_B_dma
	v_add3_u32 v18, s46, v181, -1
	v_cmp_le_i32_e32 vcc, v18, v180
	s_cbranch_vccz .Latt_B_dma
	v_max3_f32 v198, v218, v219, v220
	v_max3_f32 v210, v150, v151, v152
	v_max3_f32 v199, v221, v214, v215
	v_max3_f32 v211, v153, v146, v147
	v_max3_f32 v200, v216, v217, v222
	v_max3_f32 v212, v148, v149, v142
	v_max3_f32 v201, v223, v224, v225
	v_max3_f32 v213, v143, v144, v145
	v_max3_f32 v192, v154, v155, v156
	v_max3_f32 v193, v138, v139, v140
	v_max3_f32 v198, v198, v199, v157
	v_max3_f32 v210, v210, v211, v141
	v_max3_f32 v200, v200, v201, v192
	v_max3_f32 v212, v212, v213, v193
	v_max3_f32 v18, v198, v200, s1
	v_max3_f32 v20, v210, v212, s1
	v_mov_b32_e32 v198, v18
	v_mov_b32_e32 v210, v20
	s_nop 0
	v_permlane16_swap_b32 v18, v198
	v_permlane16_swap_b32 v20, v210
	s_nop 0
	v_max_f32_e32 v18, v18, v198
	v_max_f32_e32 v20, v20, v210
	v_mov_b32_e32 v198, v18
	v_mov_b32_e32 v210, v20
	s_nop 0
	v_permlane32_swap_b32 v18, v198
	v_permlane32_swap_b32 v20, v210
	s_nop 0
	v_max_f32_e32 v18, v18, v198
	v_max_f32_e32 v20, v20, v210
	s_cmp_eq_u32 s46, 1
	v_cmp_lt_f32_e32 vcc, 0x41000000, v18
	s_cselect_b64 vcc, exec, vcc
	s_nop 0
	v_cndmask_b32_e32 v21, 0, v18, vcc
	v_cmp_lt_f32_e32 vcc, 0x41000000, v20
	s_cselect_b64 vcc, exec, vcc
	s_nop 0
	v_cndmask_b32_e32 v191, 0, v20, vcc
	v_or_b32_e32 v18, v21, v191
	v_cmp_neq_f32_e32 vcc, 0, v18
	s_cbranch_vccz .Latt_r1_B
	v_sub_f32_e32 v218, v218, v21
	v_sub_f32_e32 v219, v219, v21
	v_sub_f32_e32 v220, v220, v21
	v_sub_f32_e32 v221, v221, v21
	v_sub_f32_e32 v214, v214, v21
	v_sub_f32_e32 v215, v215, v21
	v_sub_f32_e32 v216, v216, v21
	v_sub_f32_e32 v217, v217, v21
	v_sub_f32_e32 v222, v222, v21
	v_sub_f32_e32 v223, v223, v21
	v_sub_f32_e32 v224, v224, v21
	v_sub_f32_e32 v225, v225, v21
	v_sub_f32_e32 v154, v154, v21
	v_sub_f32_e32 v155, v155, v21
	v_sub_f32_e32 v156, v156, v21
	v_sub_f32_e32 v157, v157, v21
	v_sub_f32_e32 v150, v150, v191
	v_sub_f32_e32 v151, v151, v191
	v_sub_f32_e32 v152, v152, v191
	v_sub_f32_e32 v153, v153, v191
	v_sub_f32_e32 v146, v146, v191
	v_sub_f32_e32 v147, v147, v191
	v_sub_f32_e32 v148, v148, v191
	v_sub_f32_e32 v149, v149, v191
	v_sub_f32_e32 v142, v142, v191
	v_sub_f32_e32 v143, v143, v191
	v_sub_f32_e32 v144, v144, v191
	v_sub_f32_e32 v145, v145, v191
	v_sub_f32_e32 v138, v138, v191
	v_sub_f32_e32 v139, v139, v191
	v_sub_f32_e32 v140, v140, v191
	v_sub_f32_e32 v141, v141, v191
	v_sub_f32_e32 v18, 0, v21
	v_sub_f32_e32 v20, 0, v191
	v_min_f32_e32 v18, 0, v18
	v_min_f32_e32 v20, 0, v20
	v_exp_f32_e32 v18, v18
	v_exp_f32_e32 v20, v20
	v_add_f32_e32 v164, v164, v21
	v_add_f32_e32 v162, v162, v191
	v_sub_f32_e32 v114, v114, v21
	v_sub_f32_e32 v115, v115, v21
	v_sub_f32_e32 v116, v116, v21
	v_sub_f32_e32 v117, v117, v21
	v_sub_f32_e32 v128, v128, v191
	v_sub_f32_e32 v129, v129, v191
	v_sub_f32_e32 v130, v130, v191
	v_sub_f32_e32 v131, v131, v191
	v_pk_mul_f32 v[136:137], v[136:137], v[18:19] op_sel_hi:[1,0]
	v_pk_mul_f32 v[134:135], v[134:135], v[18:19] op_sel_hi:[1,0]
	v_pk_mul_f32 v[108:109], v[108:109], v[18:19] op_sel_hi:[1,0]
	v_pk_mul_f32 v[106:107], v[106:107], v[18:19] op_sel_hi:[1,0]
	v_pk_mul_f32 v[100:101], v[100:101], v[18:19] op_sel_hi:[1,0]
	v_pk_mul_f32 v[98:99], v[98:99], v[18:19] op_sel_hi:[1,0]
	v_pk_mul_f32 v[92:93], v[92:93], v[18:19] op_sel_hi:[1,0]
	v_pk_mul_f32 v[90:91], v[90:91], v[18:19] op_sel_hi:[1,0]
	v_pk_mul_f32 v[84:85], v[84:85], v[18:19] op_sel_hi:[1,0]
	v_pk_mul_f32 v[82:83], v[82:83], v[18:19] op_sel_hi:[1,0]
	v_pk_mul_f32 v[72:73], v[72:73], v[18:19] op_sel_hi:[1,0]
	v_pk_mul_f32 v[70:71], v[70:71], v[18:19] op_sel_hi:[1,0]
	v_pk_mul_f32 v[68:69], v[68:69], v[18:19] op_sel_hi:[1,0]
	v_pk_mul_f32 v[66:67], v[66:67], v[18:19] op_sel_hi:[1,0]
	v_pk_mul_f32 v[56:57], v[56:57], v[18:19] op_sel_hi:[1,0]
	v_pk_mul_f32 v[54:55], v[54:55], v[18:19] op_sel_hi:[1,0]
	v_pk_mul_f32 v[120:121], v[120:121], v[20:21] op_sel_hi:[1,0]
	v_pk_mul_f32 v[118:119], v[118:119], v[20:21] op_sel_hi:[1,0]
	v_pk_mul_f32 v[104:105], v[104:105], v[20:21] op_sel_hi:[1,0]
	v_pk_mul_f32 v[102:103], v[102:103], v[20:21] op_sel_hi:[1,0]
	v_pk_mul_f32 v[96:97], v[96:97], v[20:21] op_sel_hi:[1,0]
	v_pk_mul_f32 v[94:95], v[94:95], v[20:21] op_sel_hi:[1,0]
	v_pk_mul_f32 v[88:89], v[88:89], v[20:21] op_sel_hi:[1,0]
	v_pk_mul_f32 v[86:87], v[86:87], v[20:21] op_sel_hi:[1,0]
	v_pk_mul_f32 v[80:81], v[80:81], v[20:21] op_sel_hi:[1,0]
	v_pk_mul_f32 v[78:79], v[78:79], v[20:21] op_sel_hi:[1,0]
	v_pk_mul_f32 v[76:77], v[76:77], v[20:21] op_sel_hi:[1,0]
	v_pk_mul_f32 v[74:75], v[74:75], v[20:21] op_sel_hi:[1,0]
	v_pk_mul_f32 v[60:61], v[60:61], v[20:21] op_sel_hi:[1,0]
	v_pk_mul_f32 v[58:59], v[58:59], v[20:21] op_sel_hi:[1,0]
	v_pk_mul_f32 v[64:65], v[64:65], v[20:21] op_sel_hi:[1,0]
	v_pk_mul_f32 v[62:63], v[62:63], v[20:21] op_sel_hi:[1,0]
	v_mul_f32_e32 v165, v165, v18
	v_mul_f32_e32 v163, v163, v20
; DI unsigned pk2(float lo, float hi) { const f32x2 v = {lo, hi}; const bf16x2_t b = __builtin_convertvector(v, bf16x2_t); return __builtin_bit_cast(unsigned, b); }
; DI float xr16_sum(float x) { float a = x, b = x; XR_SWAP("v_permlane16_swap_b32", a, b); return a + b; }
; DI float xr32_sum(float x) { float a = x, b = x; XR_SWAP("v_permlane32_swap_b32", a, b); return a + b; }
; DI void u_attn2(Frame& F, int h, int qb, int sp, int ntile) {
;     ...
;                 float ps = 0.f; float p[16];
; #pragma unroll
;                 for (int kb = 0; kb < 4; ++kb)
; #pragma unroll
;                     for (int r = 0; r < 4; ++r) { p[kb * 4 + r] = __builtin_amdgcn_exp2f(s[kb][qq][r] - mn); ps += p[kb * 4 + r]; }
;                 ps = xr32_sum(xr16_sum(ps));
;                 lrun[qq] = lrun[qq] * alpha + ps;
; if (__builtin_amdgcn_ballot_w64(alpha != 1.0f) != 0ull) {
; #pragma unroll
;                     for (int db = 0; db < 8; ++db) o[db][qq] = o[db][qq] * alpha; }
; #pragma unroll
;                 for (int s2 = 0; s2 < 2; ++s2) { u32x4 pw; pw.x = pk2(p[8 * s2], p[8 * s2 + 1]); pw.y = pk2(p[8 * s2 + 2], p[8 * s2 + 3]); pw.z = pk2(p[8 * s2 + 4], p[8 * s2 + 5]); pw.w = pk2(p[8 * s2 + 6], p[8 * s2 + 7]); pf[qq][s2] = __builtin_bit_cast(bf16x8, pw); }
.Latt_r1_B:
	v_exp_f32_e32 v218, v218
	v_exp_f32_e32 v219, v219
	v_exp_f32_e32 v220, v220
	v_exp_f32_e32 v221, v221
	v_exp_f32_e32 v214, v214
	v_exp_f32_e32 v215, v215
	v_exp_f32_e32 v216, v216
	v_exp_f32_e32 v217, v217
	v_exp_f32_e32 v222, v222
	v_exp_f32_e32 v223, v223
	v_exp_f32_e32 v224, v224
	v_exp_f32_e32 v225, v225
	v_exp_f32_e32 v154, v154
	v_exp_f32_e32 v155, v155
	v_exp_f32_e32 v156, v156
	v_exp_f32_e32 v157, v157
	v_exp_f32_e32 v150, v150
	v_exp_f32_e32 v151, v151
	v_exp_f32_e32 v152, v152
	v_exp_f32_e32 v153, v153
	v_exp_f32_e32 v146, v146
	v_exp_f32_e32 v147, v147
	v_exp_f32_e32 v148, v148
	v_exp_f32_e32 v149, v149
	v_exp_f32_e32 v142, v142
	v_exp_f32_e32 v143, v143
	v_exp_f32_e32 v144, v144
	v_exp_f32_e32 v145, v145
	v_exp_f32_e32 v138, v138
	v_exp_f32_e32 v139, v139
	v_exp_f32_e32 v140, v140
	v_exp_f32_e32 v141, v141
	v_add_f32_e32 v198, v218, v219
	v_add_f32_e32 v199, v220, v221
	v_add_f32_e32 v200, v214, v215
	v_add_f32_e32 v201, v216, v217
	v_add_f32_e32 v210, v150, v151
	v_add_f32_e32 v211, v152, v153
	v_add_f32_e32 v212, v146, v147
	v_add_f32_e32 v213, v148, v149
	v_add_f32_e32 v198, v198, v222
	v_add_f32_e32 v199, v199, v223
	v_add_f32_e32 v200, v200, v224
	v_add_f32_e32 v201, v201, v225
	v_add_f32_e32 v210, v210, v142
	v_add_f32_e32 v211, v211, v143
	v_add_f32_e32 v212, v212, v144
	v_add_f32_e32 v213, v213, v145
	v_add_f32_e32 v198, v198, v154
	v_add_f32_e32 v199, v199, v155
	v_add_f32_e32 v200, v200, v156
	v_add_f32_e32 v201, v201, v157
	v_add_f32_e32 v210, v210, v138
	v_add_f32_e32 v211, v211, v139
	v_add_f32_e32 v212, v212, v140
	v_add_f32_e32 v213, v213, v141
	v_add_f32_e32 v198, v198, v199
	v_add_f32_e32 v200, v200, v201
	v_add_f32_e32 v210, v210, v211
	v_add_f32_e32 v212, v212, v213
	v_add_f32_e32 v198, v198, v200
	v_add_f32_e32 v210, v210, v212
	v_add_f32_e32 v165, v165, v198
	v_add_f32_e32 v163, v163, v210
	v_cvt_pk_bf16_f32 v198, v218, v219
	v_cvt_pk_bf16_f32 v199, v220, v221
	v_cvt_pk_bf16_f32 v200, v214, v215
	v_cvt_pk_bf16_f32 v201, v216, v217
	v_cvt_pk_bf16_f32 v192, v222, v223
	v_cvt_pk_bf16_f32 v193, v224, v225
	v_cvt_pk_bf16_f32 v194, v154, v155
	v_cvt_pk_bf16_f32 v195, v156, v157
	v_cvt_pk_bf16_f32 v210, v150, v151
	v_cvt_pk_bf16_f32 v211, v152, v153
	v_cvt_pk_bf16_f32 v212, v146, v147
	v_cvt_pk_bf16_f32 v213, v148, v149
	v_cvt_pk_bf16_f32 v142, v142, v143
	v_cvt_pk_bf16_f32 v143, v144, v145
	v_cvt_pk_bf16_f32 v144, v138, v139
	v_cvt_pk_bf16_f32 v145, v140, v141

; #define MFMA16(a, b, c) __builtin_amdgcn_mfma_f32_16x16x32_bf16((a), (b), (c), 0, 0, 0)
; DI void u_attn2(Frame& F, int h, int qb, int sp, int ntile) {
;     ...
;         if (kt <= cw) {
;             f32x4 s[4][2];
; #pragma unroll
;             for (int kb = 0; kb < 4; ++kb)
; #pragma unroll
;                 for (int qq = 0; qq < 2; ++qq) s[kb][qq] = (f32x4){0.f, 0.f, 0.f, 0.f};
;             {
;                 bf16x8 kfr[2][4];
; #pragma unroll
;                 for (int kb = 0; kb < 4; ++kb) kfr[0][kb] = ldfrag(Ks, 200, kb * 16, 0, lane);
; #pragma unroll
;                 for (int ks = 0; ks < 6; ++ks) {
;                     if (ks < 5) {
; #pragma unroll
;                         for (int kb = 0; kb < 4; ++kb) kfr[(ks + 1) & 1][kb] = ldfrag(Ks, 200, kb * 16, (ks + 1) * 32, lane); }
; #pragma unroll
;                     for (int kb = 0; kb < 4; ++kb)
; #pragma unroll
;                         for (int qq = 0; qq < 2; ++qq) s[kb][qq] = MFMA16(kfr[ks & 1][kb], qf[qq][ks], s[kb][qq]);
;                 }
;             }
.Latt_B_qk:
	v_cmp_lt_i32_e32 vcc, s46, v179
	s_cbranch_vccz .LBB0_2236
	v_add_u32_e32 v18, s46, v181
	v_cmp_le_i32_e32 vcc, v18, v180
	s_cbranch_vccz .LBB0_2236
	ds_read_b128 v[138:141], v112
	ds_read_b128 v[142:145], v112 offset:6656
	ds_read_b128 v[146:149], v112 offset:13312
	ds_read_b128 v[150:153], v112 offset:19968
	ds_read_b128 v[154:157], v112 offset:64
	ds_read_b128 v[192:195], v112 offset:6720
	ds_read_b128 v[210:213], v112 offset:13376
	ds_read_b128 v[214:217], v112 offset:20032
	s_waitcnt lgkmcnt(7)
	v_mfma_f32_16x16x32_bf16 v[218:221], v[138:141], v[2:5], v[114:117]
	ds_read_b128 v[244:247], v112 offset:128
	ds_read_b128 v[248:251], v112 offset:6784
	ds_read_b128 v[198:201], v112 offset:13440
	ds_read_b128 v[230:233], v112 offset:20096
	v_mov_b32_e32 v234, 0x42800000
	v_mfma_f32_16x16x32_bf16 v[138:141], v[138:141], v[30:33], v[128:131]
	s_waitcnt lgkmcnt(10)
	v_mfma_f32_16x16x32_bf16 v[222:225], v[142:145], v[2:5], v[114:117]
	v_mfma_f32_16x16x32_bf16 v[142:145], v[142:145], v[30:33], v[128:131]
	s_waitcnt lgkmcnt(9)
	v_mfma_f32_16x16x32_bf16 v[226:229], v[146:149], v[2:5], v[114:117]
	s_waitcnt lgkmcnt(7)
	v_mfma_f32_16x16x32_bf16 v[218:221], v[154:157], v[6:9], v[218:221]
	v_mfma_f32_16x16x32_bf16 v[146:149], v[146:149], v[30:33], v[128:131]
	v_mfma_f32_16x16x32_bf16 v[240:243], v[150:153], v[2:5], v[114:117]
	v_mfma_f32_16x16x32_bf16 v[150:153], v[150:153], v[30:33], v[128:131]
	v_mfma_f32_16x16x32_bf16 v[138:141], v[154:157], v[34:37], v[138:141]
	s_waitcnt lgkmcnt(6)
	v_mfma_f32_16x16x32_bf16 v[154:157], v[192:195], v[6:9], v[222:225]
	v_mfma_f32_16x16x32_bf16 v[142:145], v[192:195], v[34:37], v[142:145]
	s_waitcnt lgkmcnt(5)
	v_mfma_f32_16x16x32_bf16 v[192:195], v[210:213], v[6:9], v[226:229]
	s_waitcnt lgkmcnt(3)
	v_mfma_f32_16x16x32_bf16 v[218:221], v[244:247], v[10:13], v[218:221]
	v_mfma_f32_16x16x32_bf16 v[146:149], v[210:213], v[34:37], v[146:149]
	v_mfma_f32_16x16x32_bf16 v[210:213], v[214:217], v[6:9], v[240:243]
	v_mfma_f32_16x16x32_bf16 v[150:153], v[214:217], v[34:37], v[150:153]
	ds_read_b128 v[214:217], v112 offset:192
	ds_read_b128 v[222:225], v112 offset:6848
	ds_read_b128 v[226:229], v112 offset:13504
	ds_read_b128 v[240:243], v112 offset:20160
	v_mfma_f32_16x16x32_bf16 v[138:141], v[244:247], v[38:41], v[138:141]
	s_waitcnt lgkmcnt(6)
	v_mfma_f32_16x16x32_bf16 v[154:157], v[248:251], v[10:13], v[154:157]
	v_mfma_f32_16x16x32_bf16 v[142:145], v[248:251], v[38:41], v[142:145]
	s_waitcnt lgkmcnt(5)
	v_mfma_f32_16x16x32_bf16 v[192:195], v[198:201], v[10:13], v[192:195]
	s_waitcnt lgkmcnt(3)
	v_mfma_f32_16x16x32_bf16 v[218:221], v[214:217], v[14:17], v[218:221]
	v_mfma_f32_16x16x32_bf16 v[146:149], v[198:201], v[38:41], v[146:149]
	v_mfma_f32_16x16x32_bf16 v[198:201], v[230:233], v[10:13], v[210:213]
	v_mfma_f32_16x16x32_bf16 v[150:153], v[230:233], v[38:41], v[150:153]
	s_nop 1
	ds_read_b128 v[210:213], v112 offset:256
	ds_read_b128 v[230:233], v112 offset:6912
	ds_read_b128 v[244:247], v112 offset:13568
	ds_read_b128 v[248:251], v112 offset:20224
	v_mfma_f32_16x16x32_bf16 v[138:141], v[214:217], v[42:45], v[138:141]
	s_waitcnt lgkmcnt(6)
	v_mfma_f32_16x16x32_bf16 v[154:157], v[222:225], v[14:17], v[154:157]
	v_mfma_f32_16x16x32_bf16 v[142:145], v[222:225], v[42:45], v[142:145]
	s_waitcnt lgkmcnt(5)
	v_mfma_f32_16x16x32_bf16 v[192:195], v[226:229], v[14:17], v[192:195]
	s_waitcnt lgkmcnt(3)
	v_mfma_f32_16x16x32_bf16 v[218:221], v[210:213], v[22:25], v[218:221]
	v_mfma_f32_16x16x32_bf16 v[198:201], v[240:243], v[14:17], v[198:201]
	v_mfma_f32_16x16x32_bf16 v[150:153], v[240:243], v[42:45], v[150:153]
	v_mfma_f32_16x16x32_bf16 v[138:141], v[210:213], v[46:49], v[138:141]
	s_waitcnt lgkmcnt(2)
	v_mfma_f32_16x16x32_bf16 v[154:157], v[230:233], v[22:25], v[154:157]
	v_mfma_f32_16x16x32_bf16 v[146:149], v[226:229], v[42:45], v[146:149]
	ds_read_b128 v[214:217], v112 offset:320
	ds_read_b128 v[222:225], v112 offset:6976
	ds_read_b128 v[226:229], v112 offset:13632
	ds_read_b128 v[240:243], v112 offset:20288
	v_mfma_f32_16x16x32_bf16 v[142:145], v[230:233], v[46:49], v[142:145]
	s_waitcnt lgkmcnt(5)
	v_mfma_f32_16x16x32_bf16 v[192:195], v[244:247], v[22:25], v[192:195]
	s_waitcnt lgkmcnt(3)
	v_mfma_f32_16x16x32_bf16 v[218:221], v[214:217], v[26:29], v[218:221]
	v_mfma_f32_16x16x32_bf16 v[198:201], v[248:251], v[22:25], v[198:201]
	v_mfma_f32_16x16x32_bf16 v[230:233], v[248:251], v[46:49], v[150:153]
	v_mfma_f32_16x16x32_bf16 v[150:153], v[214:217], v[50:53], v[138:141]
	s_waitcnt lgkmcnt(2)
	v_mfma_f32_16x16x32_bf16 v[214:217], v[222:225], v[26:29], v[154:157]
	v_mfma_f32_16x16x32_bf16 v[210:213], v[244:247], v[46:49], v[146:149]
	v_mfma_f32_16x16x32_bf16 v[146:149], v[222:225], v[50:53], v[142:145]
	s_waitcnt lgkmcnt(1)
	v_mfma_f32_16x16x32_bf16 v[222:225], v[226:229], v[26:29], v[192:195]
	s_waitcnt lgkmcnt(0)
	v_mfma_f32_16x16x32_bf16 v[154:157], v[240:243], v[26:29], v[198:201]
	v_mfma_f32_16x16x32_bf16 v[138:141], v[240:243], v[50:53], v[230:233]
	s_nop 1
	v_mfma_f32_16x16x32_bf16 v[142:145], v[226:229], v[50:53], v[210:213]
	s_branch .LBB0_2236
